# d4 + fragment bank re-homing also in W_in-a and W_o loops (7 GEMM loops)
# baseline (speedup 1.0000x reference)
; #define PG8_STAGE(bufoff, gbase, voff) do { _Pragma("unroll") for (int _i = 0; _i < 2; ++_i) \
;         __builtin_amdgcn_global_load_lds((const unsigned*)((const char*)(gbase) + (voff)[_i]), (LAS unsigned*)(lds + (bufoff) + ldsw + _i * 8192), 16, 0, 0); } while (0)
; #define PG8_LDA(dst, b, h) do { _Pragma("unroll") for (int m = 0; m < 4; ++m) _Pragma("unroll") for (int k = 0; k < 2; ++k) dst[m][k] = *(const LAS bf16x8*)(lds + PG8_SA(b, h) + aoff + m * 2048 + k * 1024); } while (0)
; #define PG8_LDB(dst, b, h) do { _Pragma("unroll") for (int n = 0; n < 2; ++n) _Pragma("unroll") for (int k = 0; k < 2; ++k) dst[n][k] = *(const LAS bf16x8*)(lds + PG8_SB(b, h) + boff + n * 2048 + k * 1024); } while (0)
; #define PG8_MMA(ai, bj, At, Bt) do { __builtin_amdgcn_s_setprio(1); _Pragma("unroll") for (int m = 0; m < 4; ++m) _Pragma("unroll") for (int n = 0; n < 2; ++n) _Pragma("unroll") for (int k = 0; k < 2; ++k) \
;         acc[ai][bj][m][n] = __builtin_amdgcn_mfma_f32_16x16x32_bf16(Bt[n][k], At[m][k], acc[ai][bj][m][n], 0, 0, 0); __builtin_amdgcn_s_setprio(0); } while (0)
; #define PG8_WAIT_V(n) asm volatile("s_waitcnt vmcnt(" #n ")" ::: "memory")
; #define PG8_WAIT_L(n) asm volatile("s_waitcnt lgkmcnt(" #n ")" ::: "memory")
; #define PG8_BAR __builtin_amdgcn_s_barrier()
; template <class Epi>
; __device__ __forceinline__ void gemm_phase(LAS unsigned char* lds, const Gemm g, const StaticOrder& S, const Epi& E) {
;     ...
;             const bool last = (t == nt - 2);
;             const char* a1 = cA + (size_t)(t + 1) * kstep;
;             const char* a2 = last ? nA : cA + (size_t)(t + 2) * kstep; const char* b2 = last ? nB : cB + (size_t)(t + 2) * kstep;
;             const char* a3 = a2 + kstep; const char* b3 = b2 + kstep;
;             if constexpr (Epi::MIDK > 0) { if (t == Epi::MIDK) E.mid(acc, cur, wr, wc, fr, fq); }
;             PG8_LDB(B0, 0, 0); PG8_LDB(B1, 0, 1); PG8_SCHED; PG8_LDA(At, 0, 0); PG8_STAGE(PG8_SA(1, 1), a1 + hstep, voffA);
;             PG8_WAIT_V(8); PG8_WAIT_L(0); PG8_BAR; PG8_MMA(0, 0, At, B0); PG8_MMA(0, 1, At, B1); PG8_BAR; PG8_SCHED;
;             PG8_LDA(At, 0, 1); PG8_STAGE(PG8_SB(0, 0), b2, voffB); PG8_STAGE(PG8_SB(0, 1), b2 + hstep, voffB); PG8_STAGE(PG8_SA(0, 0), a2, voffA);
;             PG8_WAIT_V(8); PG8_WAIT_L(0); PG8_BAR; PG8_MMA(1, 0, At, B0); PG8_MMA(1, 1, At, B1); PG8_BAR; PG8_SCHED;
.LBB0_322:
	ds_read_b128 v[130:133], v191
	ds_read_b128 v[134:137], v191 offset:1024
	ds_read_b128 v[138:141], v191 offset:2048
	ds_read_b128 v[142:145], v191 offset:3072
	ds_read_b128 v[166:169], v193
	ds_read_b128 v[174:177], v193 offset:1024
	ds_read_b128 v[178:181], v193 offset:2048
	ds_read_b128 v[182:185], v193 offset:3072
	s_add_u32 s76, s88, 0xfffc0080
	s_addc_u32 s77, s89, -1
	s_cmp_eq_u32 vcc_hi, 12
	s_cselect_b32 s93, s1, s77
	s_cselect_b32 s92, s7, s76
	s_cselect_b32 s91, s9, vcc_lo
	s_cselect_b32 s90, s46, s81
	s_add_i32 m0, s96, 0xc000
	ds_read_b128 v[202:205], v194
	ds_read_b128 v[206:209], v194 offset:1024
	ds_read_b128 v[210:213], v194 offset:2048
	ds_read_b128 v[214:217], v194 offset:3072
	ds_read_b128 v[218:221], v194 offset:4096
	ds_read_b128 v[222:225], v194 offset:5120
	ds_read_b128 v[226:229], v194 offset:6144
	ds_read_b128 v[230:233], v194 offset:7168
	global_load_lds_dwordx4 v158, s[88:89]
	s_add_i32 m0, s96, 0xe000
	s_nop 0
	global_load_lds_dwordx4 v160, s[88:89]
	s_waitcnt vmcnt(8)
	s_waitcnt lgkmcnt(0)
	s_setprio 1
	s_barrier
	v_mfma_f32_16x16x32_bf16 v[126:129], v[130:133], v[202:205], v[126:129]
	v_mfma_f32_16x16x32_bf16 v[122:125], v[138:141], v[202:205], v[122:125]
	v_mfma_f32_16x16x32_bf16 v[110:113], v[130:133], v[210:213], v[110:113]
	v_mfma_f32_16x16x32_bf16 v[106:109], v[138:141], v[210:213], v[106:109]
	v_mfma_f32_16x16x32_bf16 v[94:97], v[130:133], v[218:221], v[94:97]
	v_mfma_f32_16x16x32_bf16 v[90:93], v[138:141], v[218:221], v[90:93]
	v_mfma_f32_16x16x32_bf16 v[78:81], v[130:133], v[226:229], v[78:81]
	v_mfma_f32_16x16x32_bf16 v[74:77], v[138:141], v[226:229], v[74:77]
	v_mfma_f32_16x16x32_bf16 v[126:129], v[134:137], v[206:209], v[126:129]
	v_mfma_f32_16x16x32_bf16 v[122:125], v[142:145], v[206:209], v[122:125]
	v_mfma_f32_16x16x32_bf16 v[110:113], v[134:137], v[214:217], v[110:113]
	v_mfma_f32_16x16x32_bf16 v[106:109], v[142:145], v[214:217], v[106:109]
	v_mfma_f32_16x16x32_bf16 v[94:97], v[134:137], v[222:225], v[94:97]
	v_mfma_f32_16x16x32_bf16 v[90:93], v[142:145], v[222:225], v[90:93]
	v_mfma_f32_16x16x32_bf16 v[78:81], v[134:137], v[230:233], v[78:81]
	v_mfma_f32_16x16x32_bf16 v[74:77], v[142:145], v[230:233], v[74:77]
	v_mfma_f32_16x16x32_bf16 v[118:121], v[166:169], v[202:205], v[118:121]
	v_mfma_f32_16x16x32_bf16 v[114:117], v[178:181], v[202:205], v[114:117]
	v_mfma_f32_16x16x32_bf16 v[102:105], v[166:169], v[210:213], v[102:105]
	v_mfma_f32_16x16x32_bf16 v[98:101], v[178:181], v[210:213], v[98:101]
	v_mfma_f32_16x16x32_bf16 v[86:89], v[166:169], v[218:221], v[86:89]
	v_mfma_f32_16x16x32_bf16 v[82:85], v[178:181], v[218:221], v[82:85]
	v_mfma_f32_16x16x32_bf16 v[70:73], v[166:169], v[226:229], v[70:73]
	v_mfma_f32_16x16x32_bf16 v[66:69], v[178:181], v[226:229], v[66:69]
	v_mfma_f32_16x16x32_bf16 v[118:121], v[174:177], v[206:209], v[118:121]
	v_mfma_f32_16x16x32_bf16 v[114:117], v[182:185], v[206:209], v[114:117]
	v_mfma_f32_16x16x32_bf16 v[102:105], v[174:177], v[214:217], v[102:105]
	v_mfma_f32_16x16x32_bf16 v[98:101], v[182:185], v[214:217], v[98:101]
	v_mfma_f32_16x16x32_bf16 v[86:89], v[174:177], v[222:225], v[86:89]
	v_mfma_f32_16x16x32_bf16 v[82:85], v[182:185], v[222:225], v[82:85]
	v_mfma_f32_16x16x32_bf16 v[70:73], v[174:177], v[230:233], v[70:73]
	v_mfma_f32_16x16x32_bf16 v[66:69], v[182:185], v[230:233], v[66:69]
	s_barrier
	s_setprio 0
	s_add_u32 s98, s90, s50
	s_addc_u32 s99, s91, s51
	s_add_u32 s100, s92, s50
	s_addc_u32 s101, s93, s51
	s_add_i32 s76, s42, s44
	s_mov_b32 m0, s76
	ds_read_b128 v[202:205], v194 offset:16384
	ds_read_b128 v[206:209], v194 offset:17408
	ds_read_b128 v[210:213], v194 offset:18432
	ds_read_b128 v[214:217], v194 offset:19456
	ds_read_b128 v[218:221], v194 offset:20480
	ds_read_b128 v[222:225], v194 offset:21504
	ds_read_b128 v[226:229], v194 offset:22528
	ds_read_b128 v[230:233], v194 offset:23552
	global_load_lds_dwordx4 v148, s[90:91]
	s_add_i32 m0, s76, 0x2000
	s_add_u32 s76, s90, 0x40000
	s_addc_u32 s77, s91, 0
	s_add_i32 s60, s43, s44
	global_load_lds_dwordx4 v152, s[90:91]
	s_mov_b32 m0, s60
	s_nop 0
	global_load_lds_dwordx4 v148, s[76:77]
	s_add_i32 m0, s60, 0x2000
	s_nop 0
	global_load_lds_dwordx4 v152, s[76:77]
	s_mov_b32 m0, s96
	s_nop 0
	global_load_lds_dwordx4 v146, s[92:93]
	s_mov_b32 m0, s97
	s_nop 0
	global_load_lds_dwordx4 v150, s[92:93]
	s_waitcnt vmcnt(8)
	s_waitcnt lgkmcnt(0)
	s_setprio 1
	s_barrier
	v_mfma_f32_16x16x32_bf16 v[62:65], v[130:133], v[202:205], v[62:65]
	v_mfma_f32_16x16x32_bf16 v[58:61], v[138:141], v[202:205], v[58:61]
	v_mfma_f32_16x16x32_bf16 v[46:49], v[130:133], v[210:213], v[46:49]
	v_mfma_f32_16x16x32_bf16 v[42:45], v[138:141], v[210:213], v[42:45]
	v_mfma_f32_16x16x32_bf16 v[30:33], v[130:133], v[218:221], v[30:33]
	v_mfma_f32_16x16x32_bf16 v[26:29], v[138:141], v[218:221], v[26:29]
	v_mfma_f32_16x16x32_bf16 v[14:17], v[130:133], v[226:229], v[14:17]
	v_mfma_f32_16x16x32_bf16 v[10:13], v[138:141], v[226:229], v[10:13]
	v_mfma_f32_16x16x32_bf16 v[62:65], v[134:137], v[206:209], v[62:65]
	v_mfma_f32_16x16x32_bf16 v[58:61], v[142:145], v[206:209], v[58:61]
	v_mfma_f32_16x16x32_bf16 v[46:49], v[134:137], v[214:217], v[46:49]
	v_mfma_f32_16x16x32_bf16 v[42:45], v[142:145], v[214:217], v[42:45]
	v_mfma_f32_16x16x32_bf16 v[30:33], v[134:137], v[222:225], v[30:33]
	v_mfma_f32_16x16x32_bf16 v[26:29], v[142:145], v[222:225], v[26:29]
	v_mfma_f32_16x16x32_bf16 v[14:17], v[134:137], v[230:233], v[14:17]
	v_mfma_f32_16x16x32_bf16 v[10:13], v[142:145], v[230:233], v[10:13]
	v_mfma_f32_16x16x32_bf16 v[54:57], v[166:169], v[202:205], v[54:57]
	v_mfma_f32_16x16x32_bf16 v[50:53], v[178:181], v[202:205], v[50:53]
	v_mfma_f32_16x16x32_bf16 v[38:41], v[166:169], v[210:213], v[38:41]
	v_mfma_f32_16x16x32_bf16 v[34:37], v[178:181], v[210:213], v[34:37]
	v_mfma_f32_16x16x32_bf16 v[22:25], v[166:169], v[218:221], v[22:25]
	v_mfma_f32_16x16x32_bf16 v[18:21], v[178:181], v[218:221], v[18:21]
	v_mfma_f32_16x16x32_bf16 v[6:9], v[166:169], v[226:229], v[6:9]
	v_mfma_f32_16x16x32_bf16 v[2:5], v[178:181], v[226:229], v[2:5]
	v_mfma_f32_16x16x32_bf16 v[54:57], v[174:177], v[206:209], v[54:57]
	v_mfma_f32_16x16x32_bf16 v[50:53], v[182:185], v[206:209], v[50:53]
	v_mfma_f32_16x16x32_bf16 v[38:41], v[174:177], v[214:217], v[38:41]
	v_mfma_f32_16x16x32_bf16 v[34:37], v[182:185], v[214:217], v[34:37]
	v_mfma_f32_16x16x32_bf16 v[22:25], v[174:177], v[222:225], v[22:25]
	v_mfma_f32_16x16x32_bf16 v[18:21], v[182:185], v[222:225], v[18:21]
	v_mfma_f32_16x16x32_bf16 v[6:9], v[174:177], v[230:233], v[6:9]
	v_mfma_f32_16x16x32_bf16 v[2:5], v[182:185], v[230:233], v[2:5]
	s_barrier
; #define PG8_STAGE(bufoff, gbase, voff) do { _Pragma("unroll") for (int _i = 0; _i < 2; ++_i) \
;         __builtin_amdgcn_global_load_lds((const unsigned*)((const char*)(gbase) + (voff)[_i]), (LAS unsigned*)(lds + (bufoff) + ldsw + _i * 8192), 16, 0, 0); } while (0)
; #define PG8_LDA(dst, b, h) do { _Pragma("unroll") for (int m = 0; m < 4; ++m) _Pragma("unroll") for (int k = 0; k < 2; ++k) dst[m][k] = *(const LAS bf16x8*)(lds + PG8_SA(b, h) + aoff + m * 2048 + k * 1024); } while (0)
; #define PG8_LDB(dst, b, h) do { _Pragma("unroll") for (int n = 0; n < 2; ++n) _Pragma("unroll") for (int k = 0; k < 2; ++k) dst[n][k] = *(const LAS bf16x8*)(lds + PG8_SB(b, h) + boff + n * 2048 + k * 1024); } while (0)
; #define PG8_MMA(ai, bj, At, Bt) do { __builtin_amdgcn_s_setprio(1); _Pragma("unroll") for (int m = 0; m < 4; ++m) _Pragma("unroll") for (int n = 0; n < 2; ++n) _Pragma("unroll") for (int k = 0; k < 2; ++k) \
;         acc[ai][bj][m][n] = __builtin_amdgcn_mfma_f32_16x16x32_bf16(Bt[n][k], At[m][k], acc[ai][bj][m][n], 0, 0, 0); __builtin_amdgcn_s_setprio(0); } while (0)
; #define PG8_WAIT_V(n) asm volatile("s_waitcnt vmcnt(" #n ")" ::: "memory")
; #define PG8_WAIT_L(n) asm volatile("s_waitcnt lgkmcnt(" #n ")" ::: "memory")
; #define PG8_BAR __builtin_amdgcn_s_barrier()
; #define PG8_SCHED __builtin_amdgcn_sched_barrier(0)
; template <class Epi>
; __device__ __forceinline__ void gemm_phase(LAS unsigned char* lds, const Gemm g, const StaticOrder& S, const Epi& E) {
;     ...
;             PG8_LDB(B0, 1, 0); PG8_LDB(B1, 1, 1); PG8_SCHED; PG8_LDA(At, 1, 0); PG8_STAGE(PG8_SA(0, 1), a2 + hstep, voffA);
;             PG8_WAIT_V(8); PG8_WAIT_L(0); PG8_BAR; PG8_MMA(0, 0, At, B0); PG8_MMA(0, 1, At, B1); PG8_BAR; PG8_SCHED;
;             PG8_LDA(At, 1, 1); PG8_STAGE(PG8_SB(1, 0), b3, voffB); PG8_STAGE(PG8_SB(1, 1), b3 + hstep, voffB); PG8_STAGE(PG8_SA(1, 0), a3, voffA);
;             PG8_WAIT_V(8); PG8_WAIT_L(0); PG8_BAR; PG8_MMA(1, 0, At, B0); PG8_MMA(1, 1, At, B1); PG8_BAR; PG8_SCHED;
;         }
	s_setprio 0
	s_add_i32 s60, 0, 0x18000
	s_add_i32 s61, 0, 0x1c000
	v_add_u32_e32 v142, s60, v187
	v_add_u32_e32 v182, s61, v187
	ds_read_b128 v[130:133], v142
	ds_read_b128 v[134:137], v142 offset:1024
	ds_read_b128 v[138:141], v142 offset:2048
	ds_read_b128 v[142:145], v142 offset:3072
	ds_read_b128 v[166:169], v182
	ds_read_b128 v[174:177], v182 offset:1024
	ds_read_b128 v[178:181], v182 offset:2048
	ds_read_b128 v[182:185], v182 offset:3072
	s_add_u32 s76, s92, 0x40000
	s_addc_u32 s77, s93, 0
	s_mov_b32 m0, s11
	ds_read_b128 v[202:205], v194 offset:32768
	ds_read_b128 v[206:209], v194 offset:33792
	ds_read_b128 v[210:213], v194 offset:34816
	ds_read_b128 v[214:217], v194 offset:35840
	ds_read_b128 v[218:221], v194 offset:36864
	ds_read_b128 v[222:225], v194 offset:37888
	ds_read_b128 v[226:229], v194 offset:38912
	ds_read_b128 v[230:233], v194 offset:39936
	global_load_lds_dwordx4 v146, s[76:77]
	s_mov_b32 m0, s94
	s_nop 0
	global_load_lds_dwordx4 v150, s[76:77]
	s_waitcnt vmcnt(8)
	s_waitcnt lgkmcnt(0)
	s_setprio 1
	s_barrier
	v_mfma_f32_16x16x32_bf16 v[126:129], v[130:133], v[202:205], v[126:129]
	v_mfma_f32_16x16x32_bf16 v[122:125], v[138:141], v[202:205], v[122:125]
	v_mfma_f32_16x16x32_bf16 v[110:113], v[130:133], v[210:213], v[110:113]
	v_mfma_f32_16x16x32_bf16 v[106:109], v[138:141], v[210:213], v[106:109]
	v_mfma_f32_16x16x32_bf16 v[94:97], v[130:133], v[218:221], v[94:97]
	v_mfma_f32_16x16x32_bf16 v[90:93], v[138:141], v[218:221], v[90:93]
	v_mfma_f32_16x16x32_bf16 v[78:81], v[130:133], v[226:229], v[78:81]
	v_mfma_f32_16x16x32_bf16 v[74:77], v[138:141], v[226:229], v[74:77]
	v_mfma_f32_16x16x32_bf16 v[126:129], v[134:137], v[206:209], v[126:129]
	v_mfma_f32_16x16x32_bf16 v[122:125], v[142:145], v[206:209], v[122:125]
	v_mfma_f32_16x16x32_bf16 v[110:113], v[134:137], v[214:217], v[110:113]
	v_mfma_f32_16x16x32_bf16 v[106:109], v[142:145], v[214:217], v[106:109]
	v_mfma_f32_16x16x32_bf16 v[94:97], v[134:137], v[222:225], v[94:97]
	v_mfma_f32_16x16x32_bf16 v[90:93], v[142:145], v[222:225], v[90:93]
	v_mfma_f32_16x16x32_bf16 v[78:81], v[134:137], v[230:233], v[78:81]
	v_mfma_f32_16x16x32_bf16 v[74:77], v[142:145], v[230:233], v[74:77]
	v_mfma_f32_16x16x32_bf16 v[118:121], v[166:169], v[202:205], v[118:121]
	v_mfma_f32_16x16x32_bf16 v[114:117], v[178:181], v[202:205], v[114:117]
	v_mfma_f32_16x16x32_bf16 v[102:105], v[166:169], v[210:213], v[102:105]
	v_mfma_f32_16x16x32_bf16 v[98:101], v[178:181], v[210:213], v[98:101]
	v_mfma_f32_16x16x32_bf16 v[86:89], v[166:169], v[218:221], v[86:89]
	v_mfma_f32_16x16x32_bf16 v[82:85], v[178:181], v[218:221], v[82:85]
	v_mfma_f32_16x16x32_bf16 v[70:73], v[166:169], v[226:229], v[70:73]
	v_mfma_f32_16x16x32_bf16 v[66:69], v[178:181], v[226:229], v[66:69]
	v_mfma_f32_16x16x32_bf16 v[118:121], v[174:177], v[206:209], v[118:121]
	v_mfma_f32_16x16x32_bf16 v[114:117], v[182:185], v[206:209], v[114:117]
	v_mfma_f32_16x16x32_bf16 v[102:105], v[174:177], v[214:217], v[102:105]
	v_mfma_f32_16x16x32_bf16 v[98:101], v[182:185], v[214:217], v[98:101]
	v_mfma_f32_16x16x32_bf16 v[86:89], v[174:177], v[222:225], v[86:89]
	v_mfma_f32_16x16x32_bf16 v[82:85], v[182:185], v[222:225], v[82:85]
	v_mfma_f32_16x16x32_bf16 v[70:73], v[174:177], v[230:233], v[70:73]
	v_mfma_f32_16x16x32_bf16 v[66:69], v[182:185], v[230:233], v[66:69]
	s_barrier
	s_setprio 0
	s_add_i32 s60, s60, s44
	s_mov_b32 m0, s60
	ds_read_b128 v[202:205], v194 offset:49152
	ds_read_b128 v[206:209], v194 offset:50176
	ds_read_b128 v[210:213], v194 offset:51200
	ds_read_b128 v[214:217], v194 offset:52224
	ds_read_b128 v[218:221], v194 offset:53248
	ds_read_b128 v[222:225], v194 offset:54272
	ds_read_b128 v[226:229], v194 offset:55296
	ds_read_b128 v[230:233], v194 offset:56320
	global_load_lds_dwordx4 v148, s[98:99]
	s_add_i32 m0, s60, 0x2000
	s_add_u32 s76, s90, 0x40080
	s_addc_u32 s77, s91, 0
	s_add_i32 s60, s61, s44
	global_load_lds_dwordx4 v152, s[98:99]
	s_mov_b32 m0, s60
	s_nop 0
	global_load_lds_dwordx4 v148, s[76:77]
	s_add_i32 m0, s60, 0x2000
	s_nop 0
	global_load_lds_dwordx4 v152, s[76:77]
	s_mov_b32 m0, s79
	s_nop 0
	global_load_lds_dwordx4 v146, s[100:101]
	s_mov_b32 m0, s33
	s_nop 0
	global_load_lds_dwordx4 v150, s[100:101]
	s_waitcnt vmcnt(8)
	s_waitcnt lgkmcnt(0)
	s_setprio 1
	s_barrier
	v_mfma_f32_16x16x32_bf16 v[62:65], v[130:133], v[202:205], v[62:65]
	v_mfma_f32_16x16x32_bf16 v[58:61], v[138:141], v[202:205], v[58:61]
	v_mfma_f32_16x16x32_bf16 v[46:49], v[130:133], v[210:213], v[46:49]
	v_mfma_f32_16x16x32_bf16 v[42:45], v[138:141], v[210:213], v[42:45]
	v_mfma_f32_16x16x32_bf16 v[30:33], v[130:133], v[218:221], v[30:33]
	v_mfma_f32_16x16x32_bf16 v[26:29], v[138:141], v[218:221], v[26:29]
	v_mfma_f32_16x16x32_bf16 v[14:17], v[130:133], v[226:229], v[14:17]
	v_mfma_f32_16x16x32_bf16 v[10:13], v[138:141], v[226:229], v[10:13]
	v_mfma_f32_16x16x32_bf16 v[62:65], v[134:137], v[206:209], v[62:65]
	v_mfma_f32_16x16x32_bf16 v[58:61], v[142:145], v[206:209], v[58:61]
	v_mfma_f32_16x16x32_bf16 v[46:49], v[134:137], v[214:217], v[46:49]
	v_mfma_f32_16x16x32_bf16 v[42:45], v[142:145], v[214:217], v[42:45]
	v_mfma_f32_16x16x32_bf16 v[30:33], v[134:137], v[222:225], v[30:33]
	v_mfma_f32_16x16x32_bf16 v[26:29], v[142:145], v[222:225], v[26:29]
	v_mfma_f32_16x16x32_bf16 v[14:17], v[134:137], v[230:233], v[14:17]
	v_mfma_f32_16x16x32_bf16 v[10:13], v[142:145], v[230:233], v[10:13]
	v_mfma_f32_16x16x32_bf16 v[54:57], v[166:169], v[202:205], v[54:57]
	v_mfma_f32_16x16x32_bf16 v[50:53], v[178:181], v[202:205], v[50:53]
	v_mfma_f32_16x16x32_bf16 v[38:41], v[166:169], v[210:213], v[38:41]
	v_mfma_f32_16x16x32_bf16 v[34:37], v[178:181], v[210:213], v[34:37]
	v_mfma_f32_16x16x32_bf16 v[22:25], v[166:169], v[218:221], v[22:25]
	v_mfma_f32_16x16x32_bf16 v[18:21], v[178:181], v[218:221], v[18:21]
	v_mfma_f32_16x16x32_bf16 v[6:9], v[166:169], v[226:229], v[6:9]
	v_mfma_f32_16x16x32_bf16 v[2:5], v[178:181], v[226:229], v[2:5]
	v_mfma_f32_16x16x32_bf16 v[54:57], v[174:177], v[206:209], v[54:57]
	v_mfma_f32_16x16x32_bf16 v[50:53], v[182:185], v[206:209], v[50:53]
	v_mfma_f32_16x16x32_bf16 v[38:41], v[174:177], v[214:217], v[38:41]
	v_mfma_f32_16x16x32_bf16 v[34:37], v[182:185], v[214:217], v[34:37]
	v_mfma_f32_16x16x32_bf16 v[22:25], v[174:177], v[222:225], v[22:25]
	v_mfma_f32_16x16x32_bf16 v[18:21], v[182:185], v[222:225], v[18:21]
	v_mfma_f32_16x16x32_bf16 v[6:9], v[174:177], v[230:233], v[6:9]
	v_mfma_f32_16x16x32_bf16 v[2:5], v[182:185], v[230:233], v[2:5]
	s_barrier
	s_setprio 0
	s_add_i32 vcc_hi, vcc_hi, 2
	s_add_u32 s88, s88, 0x100
	s_addc_u32 s89, s89, 0
	s_add_u32 s81, s81, 0x100
	s_addc_u32 vcc_lo, vcc_lo, 0
	s_cmp_gt_u32 vcc_hi, 13
	s_cbranch_scc0 .LBB0_322
	s_and_b64 vcc, exec, s[58:59]
	s_cbranch_vccz .LBB0_325
	s_barrier

; #define PG8_STAGE(bufoff, gbase, voff) do { _Pragma("unroll") for (int _i = 0; _i < 2; ++_i) \
;         __builtin_amdgcn_global_load_lds((const unsigned*)((const char*)(gbase) + (voff)[_i]), (LAS unsigned*)(lds + (bufoff) + ldsw + _i * 8192), 16, 0, 0); } while (0)
; #define PG8_LDA(dst, b, h) do { _Pragma("unroll") for (int m = 0; m < 4; ++m) _Pragma("unroll") for (int k = 0; k < 2; ++k) dst[m][k] = *(const LAS bf16x8*)(lds + PG8_SA(b, h) + aoff + m * 2048 + k * 1024); } while (0)
; #define PG8_LDB(dst, b, h) do { _Pragma("unroll") for (int n = 0; n < 2; ++n) _Pragma("unroll") for (int k = 0; k < 2; ++k) dst[n][k] = *(const LAS bf16x8*)(lds + PG8_SB(b, h) + boff + n * 2048 + k * 1024); } while (0)
; #define PG8_MMA(ai, bj, At, Bt) do { __builtin_amdgcn_s_setprio(1); _Pragma("unroll") for (int m = 0; m < 4; ++m) _Pragma("unroll") for (int n = 0; n < 2; ++n) _Pragma("unroll") for (int k = 0; k < 2; ++k) \
;         acc[ai][bj][m][n] = __builtin_amdgcn_mfma_f32_16x16x32_bf16(Bt[n][k], At[m][k], acc[ai][bj][m][n], 0, 0, 0); __builtin_amdgcn_s_setprio(0); } while (0)
; #define PG8_WAIT_V(n) asm volatile("s_waitcnt vmcnt(" #n ")" ::: "memory")
; #define PG8_WAIT_L(n) asm volatile("s_waitcnt lgkmcnt(" #n ")" ::: "memory")
; #define PG8_BAR __builtin_amdgcn_s_barrier()
; template <class Epi>
; __device__ __forceinline__ void gemm_phase(LAS unsigned char* lds, const Gemm g, const StaticOrder& S, const Epi& E) {
;     ...
;             const bool last = (t == nt - 2);
;             const char* a1 = cA + (size_t)(t + 1) * kstep;
;             const char* a2 = last ? nA : cA + (size_t)(t + 2) * kstep; const char* b2 = last ? nB : cB + (size_t)(t + 2) * kstep;
;             const char* a3 = a2 + kstep; const char* b3 = b2 + kstep;
;             if constexpr (Epi::MIDK > 0) { if (t == Epi::MIDK) E.mid(acc, cur, wr, wc, fr, fq); }
;             PG8_LDB(B0, 0, 0); PG8_LDB(B1, 0, 1); PG8_SCHED; PG8_LDA(At, 0, 0); PG8_STAGE(PG8_SA(1, 1), a1 + hstep, voffA);
;             PG8_WAIT_V(8); PG8_WAIT_L(0); PG8_BAR; PG8_MMA(0, 0, At, B0); PG8_MMA(0, 1, At, B1); PG8_BAR; PG8_SCHED;
;             PG8_LDA(At, 0, 1); PG8_STAGE(PG8_SB(0, 0), b2, voffB); PG8_STAGE(PG8_SB(0, 1), b2 + hstep, voffB); PG8_STAGE(PG8_SA(0, 0), a2, voffA);
;             PG8_WAIT_V(8); PG8_WAIT_L(0); PG8_BAR; PG8_MMA(1, 0, At, B0); PG8_MMA(1, 1, At, B1); PG8_BAR; PG8_SCHED;
.LBB0_785:
	ds_read_b128 v[130:133], v162
	ds_read_b128 v[134:137], v162 offset:1024
	ds_read_b128 v[154:157], v162 offset:2048
	ds_read_b128 v[166:169], v162 offset:3072
	ds_read_b128 v[174:177], v163
	ds_read_b128 v[178:181], v163 offset:1024
	ds_read_b128 v[182:185], v163 offset:2048
	ds_read_b128 v[186:189], v163 offset:3072
	s_add_u32 s40, s38, 0xfffc0080
	s_addc_u32 s41, s39, -1
	s_cmp_eq_u32 s63, 12
	s_cselect_b32 s43, s21, s41
	s_cselect_b32 s42, s27, s40
	s_cselect_b32 s41, s19, s62
	s_cselect_b32 s40, s60, s61
	s_add_i32 m0, s45, 0xc000
	ds_read_b128 v[190:193], v164
	ds_read_b128 v[194:197], v164 offset:1024
	ds_read_b128 v[198:201], v164 offset:2048
	ds_read_b128 v[202:205], v164 offset:3072
	ds_read_b128 v[206:209], v164 offset:4096
	ds_read_b128 v[210:213], v164 offset:5120
	ds_read_b128 v[214:217], v164 offset:6144
	ds_read_b128 v[218:221], v164 offset:7168
	global_load_lds_dwordx4 v146, s[38:39]
	s_add_i32 m0, s45, 0xe000
	s_nop 0
	global_load_lds_dwordx4 v148, s[38:39]
	s_waitcnt vmcnt(8)
	s_waitcnt lgkmcnt(0)
	s_setprio 1
	s_barrier
	v_mfma_f32_16x16x32_bf16 v[126:129], v[130:133], v[190:193], v[126:129]
	v_mfma_f32_16x16x32_bf16 v[122:125], v[154:157], v[190:193], v[122:125]
	v_mfma_f32_16x16x32_bf16 v[110:113], v[130:133], v[198:201], v[110:113]
	v_mfma_f32_16x16x32_bf16 v[106:109], v[154:157], v[198:201], v[106:109]
	v_mfma_f32_16x16x32_bf16 v[94:97], v[130:133], v[206:209], v[94:97]
	v_mfma_f32_16x16x32_bf16 v[90:93], v[154:157], v[206:209], v[90:93]
	v_mfma_f32_16x16x32_bf16 v[78:81], v[130:133], v[214:217], v[78:81]
	v_mfma_f32_16x16x32_bf16 v[74:77], v[154:157], v[214:217], v[74:77]
	v_mfma_f32_16x16x32_bf16 v[126:129], v[134:137], v[194:197], v[126:129]
	v_mfma_f32_16x16x32_bf16 v[122:125], v[166:169], v[194:197], v[122:125]
	v_mfma_f32_16x16x32_bf16 v[110:113], v[134:137], v[202:205], v[110:113]
	v_mfma_f32_16x16x32_bf16 v[106:109], v[166:169], v[202:205], v[106:109]
	v_mfma_f32_16x16x32_bf16 v[94:97], v[134:137], v[210:213], v[94:97]
	v_mfma_f32_16x16x32_bf16 v[90:93], v[166:169], v[210:213], v[90:93]
	v_mfma_f32_16x16x32_bf16 v[78:81], v[134:137], v[218:221], v[78:81]
	v_mfma_f32_16x16x32_bf16 v[74:77], v[166:169], v[218:221], v[74:77]
	v_mfma_f32_16x16x32_bf16 v[118:121], v[174:177], v[190:193], v[118:121]
	v_mfma_f32_16x16x32_bf16 v[114:117], v[182:185], v[190:193], v[114:117]
	v_mfma_f32_16x16x32_bf16 v[102:105], v[174:177], v[198:201], v[102:105]
	v_mfma_f32_16x16x32_bf16 v[98:101], v[182:185], v[198:201], v[98:101]
	v_mfma_f32_16x16x32_bf16 v[86:89], v[174:177], v[206:209], v[86:89]
	v_mfma_f32_16x16x32_bf16 v[82:85], v[182:185], v[206:209], v[82:85]
	v_mfma_f32_16x16x32_bf16 v[70:73], v[174:177], v[214:217], v[70:73]
	v_mfma_f32_16x16x32_bf16 v[66:69], v[182:185], v[214:217], v[66:69]
	v_mfma_f32_16x16x32_bf16 v[118:121], v[178:181], v[194:197], v[118:121]
	v_mfma_f32_16x16x32_bf16 v[114:117], v[186:189], v[194:197], v[114:117]
	v_mfma_f32_16x16x32_bf16 v[102:105], v[178:181], v[202:205], v[102:105]
	v_mfma_f32_16x16x32_bf16 v[98:101], v[186:189], v[202:205], v[98:101]
	v_mfma_f32_16x16x32_bf16 v[86:89], v[178:181], v[210:213], v[86:89]
	v_mfma_f32_16x16x32_bf16 v[82:85], v[186:189], v[210:213], v[82:85]
	v_mfma_f32_16x16x32_bf16 v[70:73], v[178:181], v[218:221], v[70:73]
	v_mfma_f32_16x16x32_bf16 v[66:69], v[186:189], v[218:221], v[66:69]
	s_barrier
	s_setprio 0
	s_add_u32 s98, s40, s12
	s_addc_u32 s99, s41, s13
	s_add_u32 s100, s42, s12
	s_addc_u32 s101, s43, s13
	s_add_i32 s64, s57, s44
	s_mov_b32 m0, s64
	ds_read_b128 v[190:193], v164 offset:16384
	ds_read_b128 v[194:197], v164 offset:17408
	ds_read_b128 v[198:201], v164 offset:18432
	ds_read_b128 v[202:205], v164 offset:19456
	ds_read_b128 v[206:209], v164 offset:20480
	ds_read_b128 v[210:213], v164 offset:21504
	ds_read_b128 v[214:217], v164 offset:22528
	ds_read_b128 v[218:221], v164 offset:23552
	global_load_lds_dwordx4 v140, s[40:41]
	s_add_i32 m0, s64, 0x2000
	s_add_u32 s64, s40, 0x40000
	s_addc_u32 s65, s41, 0
	s_add_i32 s66, s58, s44
	global_load_lds_dwordx4 v144, s[40:41]
	s_mov_b32 m0, s66
	s_nop 0
	global_load_lds_dwordx4 v140, s[64:65]
	s_add_i32 m0, s66, 0x2000
	s_nop 0
	global_load_lds_dwordx4 v144, s[64:65]
	s_mov_b32 m0, s45
	s_nop 0
	global_load_lds_dwordx4 v138, s[42:43]
	s_mov_b32 m0, s46
	s_nop 0
	global_load_lds_dwordx4 v142, s[42:43]
	s_waitcnt vmcnt(8)
	s_waitcnt lgkmcnt(0)
	s_setprio 1
	s_barrier
	v_mfma_f32_16x16x32_bf16 v[62:65], v[130:133], v[190:193], v[62:65]
	v_mfma_f32_16x16x32_bf16 v[58:61], v[154:157], v[190:193], v[58:61]
	v_mfma_f32_16x16x32_bf16 v[46:49], v[130:133], v[198:201], v[46:49]
	v_mfma_f32_16x16x32_bf16 v[42:45], v[154:157], v[198:201], v[42:45]
	v_mfma_f32_16x16x32_bf16 v[30:33], v[130:133], v[206:209], v[30:33]
	v_mfma_f32_16x16x32_bf16 v[26:29], v[154:157], v[206:209], v[26:29]
	v_mfma_f32_16x16x32_bf16 v[14:17], v[130:133], v[214:217], v[14:17]
	v_mfma_f32_16x16x32_bf16 v[10:13], v[154:157], v[214:217], v[10:13]
	v_mfma_f32_16x16x32_bf16 v[62:65], v[134:137], v[194:197], v[62:65]
	v_mfma_f32_16x16x32_bf16 v[58:61], v[166:169], v[194:197], v[58:61]
	v_mfma_f32_16x16x32_bf16 v[46:49], v[134:137], v[202:205], v[46:49]
	v_mfma_f32_16x16x32_bf16 v[42:45], v[166:169], v[202:205], v[42:45]
	v_mfma_f32_16x16x32_bf16 v[30:33], v[134:137], v[210:213], v[30:33]
	v_mfma_f32_16x16x32_bf16 v[26:29], v[166:169], v[210:213], v[26:29]
	v_mfma_f32_16x16x32_bf16 v[14:17], v[134:137], v[218:221], v[14:17]
	v_mfma_f32_16x16x32_bf16 v[10:13], v[166:169], v[218:221], v[10:13]
	v_mfma_f32_16x16x32_bf16 v[54:57], v[174:177], v[190:193], v[54:57]
	v_mfma_f32_16x16x32_bf16 v[50:53], v[182:185], v[190:193], v[50:53]
	v_mfma_f32_16x16x32_bf16 v[38:41], v[174:177], v[198:201], v[38:41]
	v_mfma_f32_16x16x32_bf16 v[34:37], v[182:185], v[198:201], v[34:37]
	v_mfma_f32_16x16x32_bf16 v[22:25], v[174:177], v[206:209], v[22:25]
	v_mfma_f32_16x16x32_bf16 v[18:21], v[182:185], v[206:209], v[18:21]
	v_mfma_f32_16x16x32_bf16 v[6:9], v[174:177], v[214:217], v[6:9]
	v_mfma_f32_16x16x32_bf16 v[2:5], v[182:185], v[214:217], v[2:5]
	v_mfma_f32_16x16x32_bf16 v[54:57], v[178:181], v[194:197], v[54:57]
	v_mfma_f32_16x16x32_bf16 v[50:53], v[186:189], v[194:197], v[50:53]
	v_mfma_f32_16x16x32_bf16 v[38:41], v[178:181], v[202:205], v[38:41]
	v_mfma_f32_16x16x32_bf16 v[34:37], v[186:189], v[202:205], v[34:37]
	v_mfma_f32_16x16x32_bf16 v[22:25], v[178:181], v[210:213], v[22:25]
	v_mfma_f32_16x16x32_bf16 v[18:21], v[186:189], v[210:213], v[18:21]
	v_mfma_f32_16x16x32_bf16 v[6:9], v[178:181], v[218:221], v[6:9]
	v_mfma_f32_16x16x32_bf16 v[2:5], v[186:189], v[218:221], v[2:5]
	s_barrier
; #define PG8_STAGE(bufoff, gbase, voff) do { _Pragma("unroll") for (int _i = 0; _i < 2; ++_i) \
;         __builtin_amdgcn_global_load_lds((const unsigned*)((const char*)(gbase) + (voff)[_i]), (LAS unsigned*)(lds + (bufoff) + ldsw + _i * 8192), 16, 0, 0); } while (0)
; #define PG8_LDA(dst, b, h) do { _Pragma("unroll") for (int m = 0; m < 4; ++m) _Pragma("unroll") for (int k = 0; k < 2; ++k) dst[m][k] = *(const LAS bf16x8*)(lds + PG8_SA(b, h) + aoff + m * 2048 + k * 1024); } while (0)
; #define PG8_LDB(dst, b, h) do { _Pragma("unroll") for (int n = 0; n < 2; ++n) _Pragma("unroll") for (int k = 0; k < 2; ++k) dst[n][k] = *(const LAS bf16x8*)(lds + PG8_SB(b, h) + boff + n * 2048 + k * 1024); } while (0)
; #define PG8_MMA(ai, bj, At, Bt) do { __builtin_amdgcn_s_setprio(1); _Pragma("unroll") for (int m = 0; m < 4; ++m) _Pragma("unroll") for (int n = 0; n < 2; ++n) _Pragma("unroll") for (int k = 0; k < 2; ++k) \
;         acc[ai][bj][m][n] = __builtin_amdgcn_mfma_f32_16x16x32_bf16(Bt[n][k], At[m][k], acc[ai][bj][m][n], 0, 0, 0); __builtin_amdgcn_s_setprio(0); } while (0)
; #define PG8_WAIT_V(n) asm volatile("s_waitcnt vmcnt(" #n ")" ::: "memory")
; #define PG8_WAIT_L(n) asm volatile("s_waitcnt lgkmcnt(" #n ")" ::: "memory")
; #define PG8_BAR __builtin_amdgcn_s_barrier()
; #define PG8_SCHED __builtin_amdgcn_sched_barrier(0)
; template <class Epi>
; __device__ __forceinline__ void gemm_phase(LAS unsigned char* lds, const Gemm g, const StaticOrder& S, const Epi& E) {
;     ...
;             PG8_LDB(B0, 1, 0); PG8_LDB(B1, 1, 1); PG8_SCHED; PG8_LDA(At, 1, 0); PG8_STAGE(PG8_SA(0, 1), a2 + hstep, voffA);
;             PG8_WAIT_V(8); PG8_WAIT_L(0); PG8_BAR; PG8_MMA(0, 0, At, B0); PG8_MMA(0, 1, At, B1); PG8_BAR; PG8_SCHED;
;             PG8_LDA(At, 1, 1); PG8_STAGE(PG8_SB(1, 0), b3, voffB); PG8_STAGE(PG8_SB(1, 1), b3 + hstep, voffB); PG8_STAGE(PG8_SA(1, 0), a3, voffA);
;             PG8_WAIT_V(8); PG8_WAIT_L(0); PG8_BAR; PG8_MMA(1, 0, At, B0); PG8_MMA(1, 1, At, B1); PG8_BAR; PG8_SCHED;
;         }
	s_setprio 0
	s_add_i32 s64, 0, 0x18000
	s_add_i32 s65, 0, 0x1c000
	v_add_u32_e32 v166, s64, v160
	v_add_u32_e32 v186, s65, v160
	ds_read_b128 v[130:133], v166
	ds_read_b128 v[134:137], v166 offset:1024
	ds_read_b128 v[154:157], v166 offset:2048
	ds_read_b128 v[166:169], v166 offset:3072
	ds_read_b128 v[174:177], v186
	ds_read_b128 v[178:181], v186 offset:1024
	ds_read_b128 v[182:185], v186 offset:2048
	ds_read_b128 v[186:189], v186 offset:3072
	s_add_u32 s42, s42, 0x40000
	s_addc_u32 s43, s43, 0
	s_mov_b32 m0, s47
	ds_read_b128 v[190:193], v164 offset:32768
	ds_read_b128 v[194:197], v164 offset:33792
	ds_read_b128 v[198:201], v164 offset:34816
	ds_read_b128 v[202:205], v164 offset:35840
	ds_read_b128 v[206:209], v164 offset:36864
	ds_read_b128 v[210:213], v164 offset:37888
	ds_read_b128 v[214:217], v164 offset:38912
	ds_read_b128 v[218:221], v164 offset:39936
	global_load_lds_dwordx4 v138, s[42:43]
	s_mov_b32 m0, s48
	s_nop 0
	global_load_lds_dwordx4 v142, s[42:43]
	s_waitcnt vmcnt(8)
	s_waitcnt lgkmcnt(0)
	s_setprio 1
	s_barrier
	v_mfma_f32_16x16x32_bf16 v[126:129], v[130:133], v[190:193], v[126:129]
	v_mfma_f32_16x16x32_bf16 v[122:125], v[154:157], v[190:193], v[122:125]
	v_mfma_f32_16x16x32_bf16 v[110:113], v[130:133], v[198:201], v[110:113]
	v_mfma_f32_16x16x32_bf16 v[106:109], v[154:157], v[198:201], v[106:109]
	v_mfma_f32_16x16x32_bf16 v[94:97], v[130:133], v[206:209], v[94:97]
	v_mfma_f32_16x16x32_bf16 v[90:93], v[154:157], v[206:209], v[90:93]
	v_mfma_f32_16x16x32_bf16 v[78:81], v[130:133], v[214:217], v[78:81]
	v_mfma_f32_16x16x32_bf16 v[74:77], v[154:157], v[214:217], v[74:77]
	v_mfma_f32_16x16x32_bf16 v[126:129], v[134:137], v[194:197], v[126:129]
	v_mfma_f32_16x16x32_bf16 v[122:125], v[166:169], v[194:197], v[122:125]
	v_mfma_f32_16x16x32_bf16 v[110:113], v[134:137], v[202:205], v[110:113]
	v_mfma_f32_16x16x32_bf16 v[106:109], v[166:169], v[202:205], v[106:109]
	v_mfma_f32_16x16x32_bf16 v[94:97], v[134:137], v[210:213], v[94:97]
	v_mfma_f32_16x16x32_bf16 v[90:93], v[166:169], v[210:213], v[90:93]
	v_mfma_f32_16x16x32_bf16 v[78:81], v[134:137], v[218:221], v[78:81]
	v_mfma_f32_16x16x32_bf16 v[74:77], v[166:169], v[218:221], v[74:77]
	v_mfma_f32_16x16x32_bf16 v[118:121], v[174:177], v[190:193], v[118:121]
	v_mfma_f32_16x16x32_bf16 v[114:117], v[182:185], v[190:193], v[114:117]
	v_mfma_f32_16x16x32_bf16 v[102:105], v[174:177], v[198:201], v[102:105]
	v_mfma_f32_16x16x32_bf16 v[98:101], v[182:185], v[198:201], v[98:101]
	v_mfma_f32_16x16x32_bf16 v[86:89], v[174:177], v[206:209], v[86:89]
	v_mfma_f32_16x16x32_bf16 v[82:85], v[182:185], v[206:209], v[82:85]
	v_mfma_f32_16x16x32_bf16 v[70:73], v[174:177], v[214:217], v[70:73]
	v_mfma_f32_16x16x32_bf16 v[66:69], v[182:185], v[214:217], v[66:69]
	v_mfma_f32_16x16x32_bf16 v[118:121], v[178:181], v[194:197], v[118:121]
	v_mfma_f32_16x16x32_bf16 v[114:117], v[186:189], v[194:197], v[114:117]
	v_mfma_f32_16x16x32_bf16 v[102:105], v[178:181], v[202:205], v[102:105]
	v_mfma_f32_16x16x32_bf16 v[98:101], v[186:189], v[202:205], v[98:101]
	v_mfma_f32_16x16x32_bf16 v[86:89], v[178:181], v[210:213], v[86:89]
	v_mfma_f32_16x16x32_bf16 v[82:85], v[186:189], v[210:213], v[82:85]
	v_mfma_f32_16x16x32_bf16 v[70:73], v[178:181], v[218:221], v[70:73]
	v_mfma_f32_16x16x32_bf16 v[66:69], v[186:189], v[218:221], v[66:69]
	s_barrier
	s_setprio 0
	s_add_i32 s42, s64, s44
	s_mov_b32 m0, s42
	ds_read_b128 v[190:193], v164 offset:49152
	ds_read_b128 v[194:197], v164 offset:50176
	ds_read_b128 v[198:201], v164 offset:51200
	ds_read_b128 v[202:205], v164 offset:52224
	ds_read_b128 v[206:209], v164 offset:53248
	ds_read_b128 v[210:213], v164 offset:54272
	ds_read_b128 v[214:217], v164 offset:55296
	ds_read_b128 v[218:221], v164 offset:56320
	global_load_lds_dwordx4 v140, s[98:99]
	s_add_i32 m0, s42, 0x2000
	s_add_u32 s40, s40, 0x40080
	s_addc_u32 s41, s41, 0
	s_add_i32 s42, s65, s44
	global_load_lds_dwordx4 v144, s[98:99]
	s_mov_b32 m0, s42
	s_nop 0
	global_load_lds_dwordx4 v140, s[40:41]
	s_add_i32 m0, s42, 0x2000
	s_nop 0
	global_load_lds_dwordx4 v144, s[40:41]
	s_mov_b32 m0, s50
	s_nop 0
	global_load_lds_dwordx4 v138, s[100:101]
	s_mov_b32 m0, s51
	s_nop 0
	global_load_lds_dwordx4 v142, s[100:101]
	s_waitcnt vmcnt(8)
	s_waitcnt lgkmcnt(0)
	s_setprio 1
	s_barrier
	v_mfma_f32_16x16x32_bf16 v[62:65], v[130:133], v[190:193], v[62:65]
	v_mfma_f32_16x16x32_bf16 v[58:61], v[154:157], v[190:193], v[58:61]
	v_mfma_f32_16x16x32_bf16 v[46:49], v[130:133], v[198:201], v[46:49]
	v_mfma_f32_16x16x32_bf16 v[42:45], v[154:157], v[198:201], v[42:45]
	v_mfma_f32_16x16x32_bf16 v[30:33], v[130:133], v[206:209], v[30:33]
	v_mfma_f32_16x16x32_bf16 v[26:29], v[154:157], v[206:209], v[26:29]
	v_mfma_f32_16x16x32_bf16 v[14:17], v[130:133], v[214:217], v[14:17]
	v_mfma_f32_16x16x32_bf16 v[10:13], v[154:157], v[214:217], v[10:13]
	v_mfma_f32_16x16x32_bf16 v[62:65], v[134:137], v[194:197], v[62:65]
	v_mfma_f32_16x16x32_bf16 v[58:61], v[166:169], v[194:197], v[58:61]
	v_mfma_f32_16x16x32_bf16 v[46:49], v[134:137], v[202:205], v[46:49]
	v_mfma_f32_16x16x32_bf16 v[42:45], v[166:169], v[202:205], v[42:45]
	v_mfma_f32_16x16x32_bf16 v[30:33], v[134:137], v[210:213], v[30:33]
	v_mfma_f32_16x16x32_bf16 v[26:29], v[166:169], v[210:213], v[26:29]
	v_mfma_f32_16x16x32_bf16 v[14:17], v[134:137], v[218:221], v[14:17]
	v_mfma_f32_16x16x32_bf16 v[10:13], v[166:169], v[218:221], v[10:13]
	v_mfma_f32_16x16x32_bf16 v[54:57], v[174:177], v[190:193], v[54:57]
	v_mfma_f32_16x16x32_bf16 v[50:53], v[182:185], v[190:193], v[50:53]
	v_mfma_f32_16x16x32_bf16 v[38:41], v[174:177], v[198:201], v[38:41]
	v_mfma_f32_16x16x32_bf16 v[34:37], v[182:185], v[198:201], v[34:37]
	v_mfma_f32_16x16x32_bf16 v[22:25], v[174:177], v[206:209], v[22:25]
	v_mfma_f32_16x16x32_bf16 v[18:21], v[182:185], v[206:209], v[18:21]
	v_mfma_f32_16x16x32_bf16 v[6:9], v[174:177], v[214:217], v[6:9]
	v_mfma_f32_16x16x32_bf16 v[2:5], v[182:185], v[214:217], v[2:5]
	v_mfma_f32_16x16x32_bf16 v[54:57], v[178:181], v[194:197], v[54:57]
	v_mfma_f32_16x16x32_bf16 v[50:53], v[186:189], v[194:197], v[50:53]
	v_mfma_f32_16x16x32_bf16 v[38:41], v[178:181], v[202:205], v[38:41]
	v_mfma_f32_16x16x32_bf16 v[34:37], v[186:189], v[202:205], v[34:37]
	v_mfma_f32_16x16x32_bf16 v[22:25], v[178:181], v[210:213], v[22:25]
	v_mfma_f32_16x16x32_bf16 v[18:21], v[186:189], v[210:213], v[18:21]
	v_mfma_f32_16x16x32_bf16 v[6:9], v[178:181], v[218:221], v[6:9]
	v_mfma_f32_16x16x32_bf16 v[2:5], v[186:189], v[218:221], v[2:5]
	s_barrier
	s_setprio 0
	s_add_i32 s63, s63, 2
	s_add_u32 s38, s38, 0x100
	s_addc_u32 s39, s39, 0
	s_add_u32 s61, s61, 0x100
	s_addc_u32 s62, s62, 0
	s_cmp_gt_u32 s63, 13
	s_cbranch_scc0 .LBB0_785
	s_and_b64 vcc, exec, s[14:15]
	s_cbranch_vccz .LBB0_788
	s_barrier
